# v18 + batched read-modify-write GEMM epilogue for w_out (x1=x+acc) and FFN-down (out+=acc): 16 loads up front, rolling add/store/load with counted vmcnt
# baseline (speedup 1.0000x reference)
; #define PG8_STAGE(bufoff, gbase, voff) do { _Pragma("unroll") for (int _i = 0; _i < 2; ++_i) \
;     __builtin_amdgcn_global_load_lds((const unsigned*)((const char*)(gbase) + (voff)[_i]), (LAS unsigned*)(lds + (bufoff) + ldsw + _i * 8192), 16, 0, 0); } while (0)
; #define PG8_LDA(dst, b, h) do { _Pragma("unroll") for (int m = 0; m < 4; ++m) _Pragma("unroll") for (int k = 0; k < 2; ++k) dst[m][k] = *(const LAS bf16x8*)(lds + PG8_SA(b, h) + aoff + m * 2048 + k * 1024); } while (0)
; #define PG8_LDB(dst, b, h) do { _Pragma("unroll") for (int n = 0; n < 2; ++n) _Pragma("unroll") for (int k = 0; k < 2; ++k) dst[n][k] = *(const LAS bf16x8*)(lds + PG8_SB(b, h) + boff + n * 2048 + k * 1024); } while (0)
; #define PG8_MMA(ai, bj, At, Bt) do { __builtin_amdgcn_s_setprio(1); _Pragma("unroll") for (int m = 0; m < 4; ++m) _Pragma("unroll") for (int n = 0; n < 2; ++n) _Pragma("unroll") for (int k = 0; k < 2; ++k) \
;     acc[ai][bj][m][n] = __builtin_amdgcn_mfma_f32_16x16x32_bf16(Bt[n][k], At[m][k], acc[ai][bj][m][n], 0, 0, 0); __builtin_amdgcn_s_setprio(0); } while (0)
; #define PG8_WAIT_L(n) asm volatile("s_waitcnt lgkmcnt(" #n ")" ::: "memory")
; #define PG8_BAR __builtin_amdgcn_s_barrier()
; #define PG8_SCHED __builtin_amdgcn_sched_barrier(0)
; template <class Epi>
; __device__ __forceinline__ void gemm_phase(LAS unsigned char* lds, const Gemm g, const Epi& E) {
;     ...
;       PG8_LDB(B0, 0, 0); PG8_SCHED; PG8_LDA(At, 0, 0); PG8_STAGE(PG8_SA(1, 1), a1 + hstepA, voffA);
;       PG8_WAIT_L(8); PG8_BAR; PG8_WAIT_L(0); PG8_MMA(0, 0, At, B0); PG8_BAR; PG8_SCHED;
;       PG8_LDB(B1, 0, 1); PG8_STAGE(PG8_SB(0, 0), b2, voffB);
;       PG8_BAR; PG8_WAIT_L(0); PG8_MMA(0, 1, At, B1); PG8_BAR;
;       PG8_LDA(At, 0, 1); PG8_STAGE(PG8_SA(0, 0), a2, voffA);
;       PG8_BAR; PG8_WAIT_L(0); PG8_MMA(1, 0, At, B0); PG8_BAR; PG8_SCHED;
.LBB0_579:
	s_add_i32 s76, s26, 2
	s_add_u32 s28, s2, 0x80
	s_addc_u32 s27, s3, 0
	s_add_i32 s83, 0, 0x10000
	v_add_u32_e32 v156, s83, v173
	ds_read_b128 v[128:131], v156
	ds_read_b128 v[148:151], v156 offset:1024
	ds_read_b128 v[152:155], v156 offset:2048
	ds_read_b128 v[156:159], v156 offset:3072
	s_cmp_eq_u32 s89, s26
	s_cselect_b32 s26, s0, s28
	s_cselect_b32 s27, s1, s27
	s_cselect_b32 s29, s21, s39
	s_cselect_b32 s28, s20, s38
	v_lshl_add_u64 v[196:197], s[2:3], 0, v[144:145]
	s_add_i32 m0, s84, 0xc000
	ds_read_b128 v[160:163], v175
	ds_read_b128 v[164:167], v175 offset:1024
	ds_read_b128 v[168:171], v175 offset:2048
	ds_read_b128 v[176:179], v175 offset:3072
	ds_read_b128 v[180:183], v175 offset:4096
	ds_read_b128 v[184:187], v175 offset:5120
	ds_read_b128 v[188:191], v175 offset:6144
	ds_read_b128 v[192:195], v175 offset:7168
	global_load_lds_dwordx4 v[196:197], off
	v_lshl_add_u64 v[196:197], s[2:3], 0, v[146:147]
	s_add_i32 m0, s84, 0xe000
	s_nop 0
	global_load_lds_dwordx4 v[196:197], off
	s_waitcnt lgkmcnt(8)
	s_barrier
	s_waitcnt lgkmcnt(0)
	s_setprio 1
	s_waitcnt lgkmcnt(0)
	v_mfma_f32_16x16x32_bf16 v[124:127], v[128:131], v[160:163], v[124:127]
	v_mfma_f32_16x16x32_bf16 v[120:123], v[152:155], v[160:163], v[120:123]
	v_mfma_f32_16x16x32_bf16 v[108:111], v[128:131], v[168:171], v[108:111]
	v_mfma_f32_16x16x32_bf16 v[104:107], v[152:155], v[168:171], v[104:107]
	v_mfma_f32_16x16x32_bf16 v[92:95], v[128:131], v[180:183], v[92:95]
	v_mfma_f32_16x16x32_bf16 v[88:91], v[152:155], v[180:183], v[88:91]
	v_mfma_f32_16x16x32_bf16 v[76:79], v[128:131], v[188:191], v[76:79]
	v_mfma_f32_16x16x32_bf16 v[72:75], v[152:155], v[188:191], v[72:75]
	v_mfma_f32_16x16x32_bf16 v[124:127], v[148:151], v[164:167], v[124:127]
	v_mfma_f32_16x16x32_bf16 v[120:123], v[156:159], v[164:167], v[120:123]
	v_mfma_f32_16x16x32_bf16 v[108:111], v[148:151], v[176:179], v[108:111]
	v_mfma_f32_16x16x32_bf16 v[104:107], v[156:159], v[176:179], v[104:107]
	v_mfma_f32_16x16x32_bf16 v[92:95], v[148:151], v[184:187], v[92:95]
	v_mfma_f32_16x16x32_bf16 v[88:91], v[156:159], v[184:187], v[88:91]
	v_mfma_f32_16x16x32_bf16 v[76:79], v[148:151], v[192:195], v[76:79]
	v_mfma_f32_16x16x32_bf16 v[72:75], v[156:159], v[192:195], v[72:75]
	s_setprio 0
	s_barrier
	s_add_i32 s94, 0, 0x14000
	s_add_i32 s83, s83, s97
	v_add_u32_e32 v208, s94, v173
	v_lshl_add_u64 v[212:213], s[28:29], 0, v[132:133]
	s_mov_b32 m0, s83
	ds_read_b128 v[196:199], v208
	ds_read_b128 v[200:203], v208 offset:1024
	ds_read_b128 v[204:207], v208 offset:2048
	ds_read_b128 v[208:211], v208 offset:3072
	global_load_lds_dwordx4 v[212:213], off
	v_lshl_add_u64 v[214:215], s[28:29], 0, v[142:143]
	s_add_i32 m0, s83, 0x2000
	s_nop 0
	global_load_lds_dwordx4 v[214:215], off
	s_barrier
	s_waitcnt lgkmcnt(0)
	s_setprio 1
	s_waitcnt lgkmcnt(0)
	v_mfma_f32_16x16x32_bf16 v[116:119], v[196:199], v[160:163], v[116:119]
	v_mfma_f32_16x16x32_bf16 v[112:115], v[204:207], v[160:163], v[112:115]
	v_mfma_f32_16x16x32_bf16 v[100:103], v[196:199], v[168:171], v[100:103]
	v_mfma_f32_16x16x32_bf16 v[96:99], v[204:207], v[168:171], v[96:99]
	v_mfma_f32_16x16x32_bf16 v[84:87], v[196:199], v[180:183], v[84:87]
	v_mfma_f32_16x16x32_bf16 v[80:83], v[204:207], v[180:183], v[80:83]
	v_mfma_f32_16x16x32_bf16 v[68:71], v[196:199], v[188:191], v[68:71]
	v_mfma_f32_16x16x32_bf16 v[64:67], v[204:207], v[188:191], v[64:67]
	v_mfma_f32_16x16x32_bf16 v[116:119], v[200:203], v[164:167], v[116:119]
	v_mfma_f32_16x16x32_bf16 v[112:115], v[208:211], v[164:167], v[112:115]
	v_mfma_f32_16x16x32_bf16 v[100:103], v[200:203], v[176:179], v[100:103]
	v_mfma_f32_16x16x32_bf16 v[96:99], v[208:211], v[176:179], v[96:99]
	v_mfma_f32_16x16x32_bf16 v[84:87], v[200:203], v[184:187], v[84:87]
	v_mfma_f32_16x16x32_bf16 v[80:83], v[208:211], v[184:187], v[80:83]
	v_mfma_f32_16x16x32_bf16 v[68:71], v[200:203], v[192:195], v[68:71]
	v_mfma_f32_16x16x32_bf16 v[64:67], v[208:211], v[192:195], v[64:67]
	s_setprio 0
	s_mov_b32 m0, s84
	v_lshl_add_u64 v[216:217], s[26:27], 0, v[138:139]
	s_barrier
	ds_read_b128 v[160:163], v175 offset:16384
	ds_read_b128 v[164:167], v175 offset:17408
	ds_read_b128 v[168:171], v175 offset:18432
	ds_read_b128 v[176:179], v175 offset:19456
	ds_read_b128 v[180:183], v175 offset:20480
	ds_read_b128 v[184:187], v175 offset:21504
	ds_read_b128 v[188:191], v175 offset:22528
	ds_read_b128 v[192:195], v175 offset:23552
	global_load_lds_dwordx4 v[216:217], off
	v_lshl_add_u64 v[218:219], s[26:27], 0, v[140:141]
	s_mov_b32 m0, s85
	s_nop 0
	global_load_lds_dwordx4 v[218:219], off
	s_barrier
	s_waitcnt lgkmcnt(0)
	s_setprio 1
	s_waitcnt lgkmcnt(0)
	v_mfma_f32_16x16x32_bf16 v[60:63], v[128:131], v[160:163], v[60:63]
	v_mfma_f32_16x16x32_bf16 v[56:59], v[152:155], v[160:163], v[56:59]
	v_mfma_f32_16x16x32_bf16 v[44:47], v[128:131], v[168:171], v[44:47]
	v_mfma_f32_16x16x32_bf16 v[40:43], v[152:155], v[168:171], v[40:43]
	v_mfma_f32_16x16x32_bf16 v[28:31], v[128:131], v[180:183], v[28:31]
	v_mfma_f32_16x16x32_bf16 v[24:27], v[152:155], v[180:183], v[24:27]
	v_mfma_f32_16x16x32_bf16 v[12:15], v[128:131], v[188:191], v[12:15]
	v_mfma_f32_16x16x32_bf16 v[8:11], v[152:155], v[188:191], v[8:11]
	v_mfma_f32_16x16x32_bf16 v[60:63], v[148:151], v[164:167], v[60:63]
	v_mfma_f32_16x16x32_bf16 v[56:59], v[156:159], v[164:167], v[56:59]
	v_mfma_f32_16x16x32_bf16 v[44:47], v[148:151], v[176:179], v[44:47]
	v_mfma_f32_16x16x32_bf16 v[40:43], v[156:159], v[176:179], v[40:43]
	v_mfma_f32_16x16x32_bf16 v[28:31], v[148:151], v[184:187], v[28:31]
	v_mfma_f32_16x16x32_bf16 v[24:27], v[156:159], v[184:187], v[24:27]
	v_mfma_f32_16x16x32_bf16 v[12:15], v[148:151], v[192:195], v[12:15]
	v_mfma_f32_16x16x32_bf16 v[8:11], v[156:159], v[192:195], v[8:11]
	s_setprio 0
	s_barrier
; #define PG8_STAGE(bufoff, gbase, voff) do { _Pragma("unroll") for (int _i = 0; _i < 2; ++_i) \
;     __builtin_amdgcn_global_load_lds((const unsigned*)((const char*)(gbase) + (voff)[_i]), (LAS unsigned*)(lds + (bufoff) + ldsw + _i * 8192), 16, 0, 0); } while (0)
; #define PG8_LDA(dst, b, h) do { _Pragma("unroll") for (int m = 0; m < 4; ++m) _Pragma("unroll") for (int k = 0; k < 2; ++k) dst[m][k] = *(const LAS bf16x8*)(lds + PG8_SA(b, h) + aoff + m * 2048 + k * 1024); } while (0)
; #define PG8_LDB(dst, b, h) do { _Pragma("unroll") for (int n = 0; n < 2; ++n) _Pragma("unroll") for (int k = 0; k < 2; ++k) dst[n][k] = *(const LAS bf16x8*)(lds + PG8_SB(b, h) + boff + n * 2048 + k * 1024); } while (0)
; #define PG8_MMA(ai, bj, At, Bt) do { __builtin_amdgcn_s_setprio(1); _Pragma("unroll") for (int m = 0; m < 4; ++m) _Pragma("unroll") for (int n = 0; n < 2; ++n) _Pragma("unroll") for (int k = 0; k < 2; ++k) \
;     acc[ai][bj][m][n] = __builtin_amdgcn_mfma_f32_16x16x32_bf16(Bt[n][k], At[m][k], acc[ai][bj][m][n], 0, 0, 0); __builtin_amdgcn_s_setprio(0); } while (0)
; #define PG8_WAIT_V(n) asm volatile("s_waitcnt vmcnt(" #n ")" ::: "memory")
; #define PG8_WAIT_L(n) asm volatile("s_waitcnt lgkmcnt(" #n ")" ::: "memory")
; #define PG8_BAR __builtin_amdgcn_s_barrier()
; #define PG8_SCHED __builtin_amdgcn_sched_barrier(0)
; template <class Epi>
; __device__ __forceinline__ void gemm_phase(LAS unsigned char* lds, const Gemm g, const Epi& E) {
;     ...
;       PG8_STAGE(PG8_SB(0, 1), b2 + hstepB, voffB);
;       PG8_WAIT_V(6); PG8_BAR; PG8_MMA(1, 1, At, B1); PG8_BAR;
;       PG8_LDB(B0, 1, 0); PG8_SCHED; PG8_LDA(At, 1, 0); PG8_STAGE(PG8_SA(0, 1), a2 + hstepA, voffA);
;       PG8_WAIT_L(8); PG8_BAR; PG8_WAIT_L(0); PG8_MMA(0, 0, At, B0); PG8_BAR; PG8_SCHED;
;       PG8_LDB(B1, 1, 1); PG8_STAGE(PG8_SB(1, 0), b3, voffB);
;       PG8_BAR; PG8_WAIT_L(0); PG8_MMA(0, 1, At, B1); PG8_BAR;
	s_add_u32 s28, s28, s95
	s_addc_u32 s29, s29, 0
	s_add_i32 s83, s94, s97
	v_lshl_add_u64 v[220:221], s[28:29], 0, v[132:133]
	s_mov_b32 m0, s83
	v_lshl_add_u64 v[222:223], s[28:29], 0, v[142:143]
	global_load_lds_dwordx4 v[220:221], off
	s_add_i32 m0, s83, 0x2000
	s_nop 0
	global_load_lds_dwordx4 v[222:223], off
	s_waitcnt vmcnt(6)
	s_barrier
	s_setprio 1
	v_mfma_f32_16x16x32_bf16 v[52:55], v[196:199], v[160:163], v[52:55]
	v_mfma_f32_16x16x32_bf16 v[48:51], v[204:207], v[160:163], v[48:51]
	v_mfma_f32_16x16x32_bf16 v[36:39], v[196:199], v[168:171], v[36:39]
	v_mfma_f32_16x16x32_bf16 v[32:35], v[204:207], v[168:171], v[32:35]
	v_mfma_f32_16x16x32_bf16 v[20:23], v[196:199], v[180:183], v[20:23]
	v_mfma_f32_16x16x32_bf16 v[16:19], v[204:207], v[180:183], v[16:19]
	v_mfma_f32_16x16x32_bf16 v[4:7], v[196:199], v[188:191], v[4:7]
	v_mfma_f32_16x16x32_bf16 v[0:3], v[204:207], v[188:191], v[0:3]
	v_mfma_f32_16x16x32_bf16 v[52:55], v[200:203], v[164:167], v[52:55]
	v_mfma_f32_16x16x32_bf16 v[48:51], v[208:211], v[164:167], v[48:51]
	v_mfma_f32_16x16x32_bf16 v[36:39], v[200:203], v[176:179], v[36:39]
	v_mfma_f32_16x16x32_bf16 v[32:35], v[208:211], v[176:179], v[32:35]
	v_mfma_f32_16x16x32_bf16 v[20:23], v[200:203], v[184:187], v[20:23]
	v_mfma_f32_16x16x32_bf16 v[16:19], v[208:211], v[184:187], v[16:19]
	v_mfma_f32_16x16x32_bf16 v[4:7], v[200:203], v[192:195], v[4:7]
	v_mfma_f32_16x16x32_bf16 v[0:3], v[208:211], v[192:195], v[0:3]
	s_setprio 0
	s_add_i32 s28, 0, 0x18000
	v_add_u32_e32 v156, s28, v173
	s_barrier
	ds_read_b128 v[128:131], v156
	ds_read_b128 v[148:151], v156 offset:1024
	ds_read_b128 v[152:155], v156 offset:2048
	ds_read_b128 v[156:159], v156 offset:3072
	s_add_u32 s26, s26, s56
	s_addc_u32 s27, s27, 0
	s_mov_b32 m0, s86
	v_lshl_add_u64 v[196:197], s[26:27], 0, v[138:139]
	ds_read_b128 v[160:163], v175 offset:32768
	ds_read_b128 v[164:167], v175 offset:33792
	ds_read_b128 v[168:171], v175 offset:34816
	ds_read_b128 v[176:179], v175 offset:35840
	ds_read_b128 v[180:183], v175 offset:36864
	ds_read_b128 v[184:187], v175 offset:37888
	ds_read_b128 v[188:191], v175 offset:38912
	ds_read_b128 v[192:195], v175 offset:39936
	global_load_lds_dwordx4 v[196:197], off
	v_lshl_add_u64 v[196:197], s[26:27], 0, v[140:141]
	s_mov_b32 m0, s87
	s_nop 0
	global_load_lds_dwordx4 v[196:197], off
	s_waitcnt lgkmcnt(8)
	s_barrier
	s_waitcnt lgkmcnt(0)
	s_setprio 1
	s_waitcnt lgkmcnt(0)
	v_mfma_f32_16x16x32_bf16 v[124:127], v[128:131], v[160:163], v[124:127]
	v_mfma_f32_16x16x32_bf16 v[120:123], v[152:155], v[160:163], v[120:123]
	v_mfma_f32_16x16x32_bf16 v[108:111], v[128:131], v[168:171], v[108:111]
	v_mfma_f32_16x16x32_bf16 v[104:107], v[152:155], v[168:171], v[104:107]
	v_mfma_f32_16x16x32_bf16 v[92:95], v[128:131], v[180:183], v[92:95]
	v_mfma_f32_16x16x32_bf16 v[88:91], v[152:155], v[180:183], v[88:91]
	v_mfma_f32_16x16x32_bf16 v[76:79], v[128:131], v[188:191], v[76:79]
	v_mfma_f32_16x16x32_bf16 v[72:75], v[152:155], v[188:191], v[72:75]
	v_mfma_f32_16x16x32_bf16 v[124:127], v[148:151], v[164:167], v[124:127]
	v_mfma_f32_16x16x32_bf16 v[120:123], v[156:159], v[164:167], v[120:123]
	v_mfma_f32_16x16x32_bf16 v[108:111], v[148:151], v[176:179], v[108:111]
	v_mfma_f32_16x16x32_bf16 v[104:107], v[156:159], v[176:179], v[104:107]
	v_mfma_f32_16x16x32_bf16 v[92:95], v[148:151], v[184:187], v[92:95]
	v_mfma_f32_16x16x32_bf16 v[88:91], v[156:159], v[184:187], v[88:91]
	v_mfma_f32_16x16x32_bf16 v[76:79], v[148:151], v[192:195], v[76:79]
	v_mfma_f32_16x16x32_bf16 v[72:75], v[156:159], v[192:195], v[72:75]
	s_setprio 0
	s_barrier
	s_add_i32 s26, 0, 0x1c000
	s_add_i32 s27, s28, s97
	v_add_u32_e32 v208, s26, v173
	v_lshl_add_u64 v[212:213], v[212:213], 0, s[22:23]
	s_mov_b32 m0, s27
	ds_read_b128 v[196:199], v208
	ds_read_b128 v[200:203], v208 offset:1024
	ds_read_b128 v[204:207], v208 offset:2048
	ds_read_b128 v[208:211], v208 offset:3072
	global_load_lds_dwordx4 v[212:213], off
	v_lshl_add_u64 v[212:213], v[214:215], 0, s[22:23]
	s_add_i32 m0, s27, 0x2000
	s_nop 0
	global_load_lds_dwordx4 v[212:213], off
	s_barrier
	s_waitcnt lgkmcnt(0)
	s_setprio 1
	s_waitcnt lgkmcnt(0)
	v_mfma_f32_16x16x32_bf16 v[116:119], v[196:199], v[160:163], v[116:119]
	v_mfma_f32_16x16x32_bf16 v[112:115], v[204:207], v[160:163], v[112:115]
	v_mfma_f32_16x16x32_bf16 v[100:103], v[196:199], v[168:171], v[100:103]
	v_mfma_f32_16x16x32_bf16 v[96:99], v[204:207], v[168:171], v[96:99]
	v_mfma_f32_16x16x32_bf16 v[84:87], v[196:199], v[180:183], v[84:87]
	v_mfma_f32_16x16x32_bf16 v[80:83], v[204:207], v[180:183], v[80:83]
	v_mfma_f32_16x16x32_bf16 v[68:71], v[196:199], v[188:191], v[68:71]
	v_mfma_f32_16x16x32_bf16 v[64:67], v[204:207], v[188:191], v[64:67]
	v_mfma_f32_16x16x32_bf16 v[116:119], v[200:203], v[164:167], v[116:119]
	v_mfma_f32_16x16x32_bf16 v[112:115], v[208:211], v[164:167], v[112:115]
	v_mfma_f32_16x16x32_bf16 v[100:103], v[200:203], v[176:179], v[100:103]
	v_mfma_f32_16x16x32_bf16 v[96:99], v[208:211], v[176:179], v[96:99]
	v_mfma_f32_16x16x32_bf16 v[84:87], v[200:203], v[184:187], v[84:87]
	v_mfma_f32_16x16x32_bf16 v[80:83], v[208:211], v[184:187], v[80:83]
	v_mfma_f32_16x16x32_bf16 v[68:71], v[200:203], v[192:195], v[68:71]
	v_mfma_f32_16x16x32_bf16 v[64:67], v[208:211], v[192:195], v[64:67]
	s_setprio 0
	s_mov_b32 m0, s74
	v_lshl_add_u64 v[212:213], v[216:217], 0, s[22:23]
	s_barrier
; #define PG8_STAGE(bufoff, gbase, voff) do { _Pragma("unroll") for (int _i = 0; _i < 2; ++_i) \
;     __builtin_amdgcn_global_load_lds((const unsigned*)((const char*)(gbase) + (voff)[_i]), (LAS unsigned*)(lds + (bufoff) + ldsw + _i * 8192), 16, 0, 0); } while (0)
; #define PG8_LDA(dst, b, h) do { _Pragma("unroll") for (int m = 0; m < 4; ++m) _Pragma("unroll") for (int k = 0; k < 2; ++k) dst[m][k] = *(const LAS bf16x8*)(lds + PG8_SA(b, h) + aoff + m * 2048 + k * 1024); } while (0)
; #define PG8_MMA(ai, bj, At, Bt) do { __builtin_amdgcn_s_setprio(1); _Pragma("unroll") for (int m = 0; m < 4; ++m) _Pragma("unroll") for (int n = 0; n < 2; ++n) _Pragma("unroll") for (int k = 0; k < 2; ++k) \
;     acc[ai][bj][m][n] = __builtin_amdgcn_mfma_f32_16x16x32_bf16(Bt[n][k], At[m][k], acc[ai][bj][m][n], 0, 0, 0); __builtin_amdgcn_s_setprio(0); } while (0)
; #define PG8_WAIT_V(n) asm volatile("s_waitcnt vmcnt(" #n ")" ::: "memory")
; #define PG8_WAIT_L(n) asm volatile("s_waitcnt lgkmcnt(" #n ")" ::: "memory")
; #define PG8_BAR __builtin_amdgcn_s_barrier()
; #define PG8_SCHED __builtin_amdgcn_sched_barrier(0)
; template <class Epi>
; __device__ __forceinline__ void gemm_phase(LAS unsigned char* lds, const Gemm g, const Epi& E) {
;     ...
;       PG8_LDA(At, 1, 1); PG8_STAGE(PG8_SA(1, 0), a3, voffA);
;       PG8_BAR; PG8_WAIT_L(0); PG8_MMA(1, 0, At, B0); PG8_BAR; PG8_SCHED;
;       PG8_STAGE(PG8_SB(1, 1), b3 + hstepB, voffB);
;       PG8_WAIT_V(6); PG8_BAR; PG8_MMA(1, 1, At, B1); PG8_BAR;
;     }
;     {
; #pragma unroll
;       for (int ai = 0; ai < 2; ++ai)
; #pragma unroll
;         for (int m = 0; m < 4; ++m)
; #pragma unroll
;           for (int bj = 0; bj < 2; ++bj)
;           { E.st2(cur.w, cur.pm * BM + ai * HALF + wr * 64 + m * 16 + fr, cur.pn * BM + bj * HALF + wc * 32 + 8 * fq, acc[ai][bj][m][0], acc[ai][bj][m][1]); if (bj == 1 && (m & 1)) asm volatile("" ::: "memory"); }
	ds_read_b128 v[160:163], v175 offset:49152
	ds_read_b128 v[164:167], v175 offset:50176
	ds_read_b128 v[168:171], v175 offset:51200
	ds_read_b128 v[176:179], v175 offset:52224
	ds_read_b128 v[180:183], v175 offset:53248
	ds_read_b128 v[184:187], v175 offset:54272
	ds_read_b128 v[188:191], v175 offset:55296
	ds_read_b128 v[192:195], v175 offset:56320
	global_load_lds_dwordx4 v[212:213], off
	v_lshl_add_u64 v[212:213], v[218:219], 0, s[22:23]
	s_mov_b32 m0, s78
	s_nop 0
	global_load_lds_dwordx4 v[212:213], off
	s_barrier
	s_waitcnt lgkmcnt(0)
	s_setprio 1
	s_waitcnt lgkmcnt(0)
	v_mfma_f32_16x16x32_bf16 v[60:63], v[128:131], v[160:163], v[60:63]
	v_mfma_f32_16x16x32_bf16 v[56:59], v[152:155], v[160:163], v[56:59]
	v_mfma_f32_16x16x32_bf16 v[44:47], v[128:131], v[168:171], v[44:47]
	v_mfma_f32_16x16x32_bf16 v[40:43], v[152:155], v[168:171], v[40:43]
	v_mfma_f32_16x16x32_bf16 v[28:31], v[128:131], v[180:183], v[28:31]
	v_mfma_f32_16x16x32_bf16 v[24:27], v[152:155], v[180:183], v[24:27]
	v_mfma_f32_16x16x32_bf16 v[12:15], v[128:131], v[188:191], v[12:15]
	v_mfma_f32_16x16x32_bf16 v[8:11], v[152:155], v[188:191], v[8:11]
	v_mfma_f32_16x16x32_bf16 v[60:63], v[148:151], v[164:167], v[60:63]
	v_mfma_f32_16x16x32_bf16 v[56:59], v[156:159], v[164:167], v[56:59]
	v_mfma_f32_16x16x32_bf16 v[44:47], v[148:151], v[176:179], v[44:47]
	v_mfma_f32_16x16x32_bf16 v[40:43], v[156:159], v[176:179], v[40:43]
	v_mfma_f32_16x16x32_bf16 v[28:31], v[148:151], v[184:187], v[28:31]
	v_mfma_f32_16x16x32_bf16 v[24:27], v[156:159], v[184:187], v[24:27]
	v_mfma_f32_16x16x32_bf16 v[12:15], v[148:151], v[192:195], v[12:15]
	v_mfma_f32_16x16x32_bf16 v[8:11], v[156:159], v[192:195], v[8:11]
	s_setprio 0
	s_barrier
	s_add_i32 s26, s26, s97
	v_lshl_add_u64 v[128:129], v[220:221], 0, s[22:23]
	s_mov_b32 m0, s26
	s_nop 0
	global_load_lds_dwordx4 v[128:129], off
	v_lshl_add_u64 v[128:129], v[222:223], 0, s[22:23]
	s_add_i32 m0, s26, 0x2000
	s_nop 0
	global_load_lds_dwordx4 v[128:129], off
	s_waitcnt vmcnt(6)
	s_barrier
	s_setprio 1
	v_mfma_f32_16x16x32_bf16 v[52:55], v[196:199], v[160:163], v[52:55]
	v_mfma_f32_16x16x32_bf16 v[48:51], v[204:207], v[160:163], v[48:51]
	v_mfma_f32_16x16x32_bf16 v[36:39], v[196:199], v[168:171], v[36:39]
	v_mfma_f32_16x16x32_bf16 v[32:35], v[204:207], v[168:171], v[32:35]
	v_mfma_f32_16x16x32_bf16 v[20:23], v[196:199], v[180:183], v[20:23]
	v_mfma_f32_16x16x32_bf16 v[16:19], v[204:207], v[180:183], v[16:19]
	v_mfma_f32_16x16x32_bf16 v[4:7], v[196:199], v[188:191], v[4:7]
	v_mfma_f32_16x16x32_bf16 v[0:3], v[204:207], v[188:191], v[0:3]
	v_mfma_f32_16x16x32_bf16 v[52:55], v[200:203], v[164:167], v[52:55]
	v_mfma_f32_16x16x32_bf16 v[48:51], v[208:211], v[164:167], v[48:51]
	v_mfma_f32_16x16x32_bf16 v[36:39], v[200:203], v[176:179], v[36:39]
	v_mfma_f32_16x16x32_bf16 v[32:35], v[208:211], v[176:179], v[32:35]
	v_mfma_f32_16x16x32_bf16 v[20:23], v[200:203], v[184:187], v[20:23]
	v_mfma_f32_16x16x32_bf16 v[16:19], v[208:211], v[184:187], v[16:19]
	v_mfma_f32_16x16x32_bf16 v[4:7], v[200:203], v[192:195], v[4:7]
	v_mfma_f32_16x16x32_bf16 v[0:3], v[208:211], v[192:195], v[0:3]
	s_setprio 0
	s_add_u32 s2, s2, 0x100
	s_addc_u32 s3, s3, 0
	s_add_u32 s38, s38, 0x100
	s_addc_u32 s39, s39, 0
	s_cmp_ge_u32 s76, s72
	s_mov_b32 s26, s76
	s_barrier
	s_cbranch_scc0 .LBB0_579
	s_lshl_b32 s28, s53, 8
	v_lshl_add_u32 v150, s75, 8, v172
	s_cmp_eq_u32 s12, 0
	v_ashrrev_i32_e32 v151, 31, v150
	v_mad_i64_i32 v[164:165], s[2:3], v150, s54, 0
	v_mad_i64_i32 v[154:155], s[2:3], v150, s33, 0
	s_cselect_b32 s29, s40, s41
	v_lshlrev_b64 v[162:163], 10, v[150:151]
	v_cmp_gt_i32_e64 s[38:39], s92, v150
	v_lshlrev_b64 v[152:153], 12, v[150:151]
	v_or_b32_e32 v148, s28, v174
	s_cmp_eq_u32 s29, 7
	s_cbranch_scc1 .Lepi7
	s_cmp_eq_u32 s29, 5
	s_cbranch_scc1 .Lepi5
	s_cmp_lt_i32 s29, 4
	s_mov_b64 s[2:3], -1
	s_cbranch_scc1 .LBB0_593
	s_cmp_lt_i32 s29, 6
	s_cbranch_scc1 .LBB0_587
	s_cmp_gt_i32 s29, 6
	s_cbranch_scc0 .LBB0_584
	v_lshl_add_u64 v[128:129], s[58:59], 0, v[152:153]
	v_ashrrev_i32_e32 v149, 31, v148
	v_lshl_add_u64 v[160:161], v[148:149], 2, v[128:129]
	global_load_dwordx4 v[128:131], v[160:161], off nt
	global_load_dwordx4 v[156:159], v[160:161], off offset:16 nt
	s_mov_b64 s[2:3], 0
	s_waitcnt vmcnt(0)
	v_pk_add_f32 v[130:131], v[126:127], v[130:131]
	v_pk_add_f32 v[128:129], v[124:125], v[128:129]
	v_pk_add_f32 v[158:159], v[122:123], v[158:159]
	v_pk_add_f32 v[156:157], v[120:121], v[156:157]
	global_store_dwordx4 v[160:161], v[128:131], off nt
	global_store_dwordx4 v[160:161], v[156:159], off offset:16 nt

; template <class Epi>
; __device__ __forceinline__ void gemm_phase(LAS unsigned char* lds, const Gemm g, const Epi& E) {
;     ...
;       for (int ai = 0; ai < 2; ++ai)
; #pragma unroll
;         for (int m = 0; m < 4; ++m)
; #pragma unroll
;           for (int bj = 0; bj < 2; ++bj)
;           { E.st2(cur.w, cur.pm * BM + ai * HALF + wr * 64 + m * 16 + fr, cur.pn * BM + bj * HALF + wc * 32 + 8 * fq, acc[ai][bj][m][0], acc[ai][bj][m][1]); if (bj == 1 && (m & 1)) asm volatile("" ::: "memory"); }
.Lepi7:
	v_lshlrev_b32_e32 v176, 12, v150
	v_lshl_add_u32 v176, v148, 2, v176
	v_add_u32_e32 v177, 0x10000, v176
	v_add_u32_e32 v178, 0x20000, v176
	v_add_u32_e32 v179, 0x30000, v176
	v_add_u32_e32 v180, 0x80000, v176
	v_add_u32_e32 v181, 0x90000, v176
	v_add_u32_e32 v182, 0xa0000, v176
	v_add_u32_e32 v183, 0xb0000, v176
	global_load_dwordx4 v[184:187], v176, s[58:59] nt
	global_load_dwordx4 v[188:191], v176, s[58:59] offset:16 nt
	global_load_dwordx4 v[192:195], v176, s[58:59] offset:512 nt
	global_load_dwordx4 v[196:199], v176, s[58:59] offset:528 nt
	global_load_dwordx4 v[200:203], v177, s[58:59] nt
	global_load_dwordx4 v[204:207], v177, s[58:59] offset:16 nt
	global_load_dwordx4 v[208:211], v177, s[58:59] offset:512 nt
	global_load_dwordx4 v[212:215], v177, s[58:59] offset:528 nt
	global_load_dwordx4 v[216:219], v178, s[58:59] nt
	global_load_dwordx4 v[220:223], v178, s[58:59] offset:16 nt
	global_load_dwordx4 v[152:155], v178, s[58:59] offset:512 nt
	global_load_dwordx4 v[156:159], v178, s[58:59] offset:528 nt
	global_load_dwordx4 v[160:163], v179, s[58:59] nt
	global_load_dwordx4 v[164:167], v179, s[58:59] offset:16 nt
	global_load_dwordx4 v[168:171], v179, s[58:59] offset:512 nt
	global_load_dwordx4 v[128:131], v179, s[58:59] offset:528 nt
	s_waitcnt vmcnt(14)
	v_pk_add_f32 v[186:187], v[126:127], v[186:187]
	v_pk_add_f32 v[184:185], v[124:125], v[184:185]
	v_pk_add_f32 v[190:191], v[122:123], v[190:191]
	v_pk_add_f32 v[188:189], v[120:121], v[188:189]
	global_store_dwordx4 v176, v[184:187], s[58:59] nt
	global_store_dwordx4 v176, v[188:191], s[58:59] offset:16 nt
	global_load_dwordx4 v[124:127], v180, s[58:59] nt
	global_load_dwordx4 v[120:123], v180, s[58:59] offset:16 nt
	s_waitcnt vmcnt(16)
	v_pk_add_f32 v[194:195], v[118:119], v[194:195]
	v_pk_add_f32 v[192:193], v[116:117], v[192:193]
	v_pk_add_f32 v[198:199], v[114:115], v[198:199]
	v_pk_add_f32 v[196:197], v[112:113], v[196:197]
	global_store_dwordx4 v176, v[192:195], s[58:59] offset:512 nt
	global_store_dwordx4 v176, v[196:199], s[58:59] offset:528 nt
	global_load_dwordx4 v[116:119], v180, s[58:59] offset:512 nt
	global_load_dwordx4 v[112:115], v180, s[58:59] offset:528 nt
	s_waitcnt vmcnt(18)
	v_pk_add_f32 v[202:203], v[110:111], v[202:203]
	v_pk_add_f32 v[200:201], v[108:109], v[200:201]
	v_pk_add_f32 v[206:207], v[106:107], v[206:207]
	v_pk_add_f32 v[204:205], v[104:105], v[204:205]
	global_store_dwordx4 v177, v[200:203], s[58:59] nt
	global_store_dwordx4 v177, v[204:207], s[58:59] offset:16 nt
	global_load_dwordx4 v[108:111], v181, s[58:59] nt
	global_load_dwordx4 v[104:107], v181, s[58:59] offset:16 nt
	s_waitcnt vmcnt(20)
	v_pk_add_f32 v[210:211], v[102:103], v[210:211]
	v_pk_add_f32 v[208:209], v[100:101], v[208:209]
	v_pk_add_f32 v[214:215], v[98:99], v[214:215]
	v_pk_add_f32 v[212:213], v[96:97], v[212:213]
	global_store_dwordx4 v177, v[208:211], s[58:59] offset:512 nt
	global_store_dwordx4 v177, v[212:215], s[58:59] offset:528 nt
	global_load_dwordx4 v[100:103], v181, s[58:59] offset:512 nt
	global_load_dwordx4 v[96:99], v181, s[58:59] offset:528 nt
	s_waitcnt vmcnt(22)
	v_pk_add_f32 v[218:219], v[94:95], v[218:219]
	v_pk_add_f32 v[216:217], v[92:93], v[216:217]
	v_pk_add_f32 v[222:223], v[90:91], v[222:223]
	v_pk_add_f32 v[220:221], v[88:89], v[220:221]
	global_store_dwordx4 v178, v[216:219], s[58:59] nt
	global_store_dwordx4 v178, v[220:223], s[58:59] offset:16 nt
	global_load_dwordx4 v[92:95], v182, s[58:59] nt
	global_load_dwordx4 v[88:91], v182, s[58:59] offset:16 nt
	s_waitcnt vmcnt(24)
	v_pk_add_f32 v[154:155], v[86:87], v[154:155]
	v_pk_add_f32 v[152:153], v[84:85], v[152:153]
	v_pk_add_f32 v[158:159], v[82:83], v[158:159]
	v_pk_add_f32 v[156:157], v[80:81], v[156:157]
	global_store_dwordx4 v178, v[152:155], s[58:59] offset:512 nt
	global_store_dwordx4 v178, v[156:159], s[58:59] offset:528 nt
	global_load_dwordx4 v[84:87], v182, s[58:59] offset:512 nt
	global_load_dwordx4 v[80:83], v182, s[58:59] offset:528 nt
	s_waitcnt vmcnt(26)
	v_pk_add_f32 v[162:163], v[78:79], v[162:163]
	v_pk_add_f32 v[160:161], v[76:77], v[160:161]
	v_pk_add_f32 v[166:167], v[74:75], v[166:167]
	v_pk_add_f32 v[164:165], v[72:73], v[164:165]
	global_store_dwordx4 v179, v[160:163], s[58:59] nt
	global_store_dwordx4 v179, v[164:167], s[58:59] offset:16 nt
	global_load_dwordx4 v[76:79], v183, s[58:59] nt
	global_load_dwordx4 v[72:75], v183, s[58:59] offset:16 nt
	s_waitcnt vmcnt(28)
	v_pk_add_f32 v[170:171], v[70:71], v[170:171]
	v_pk_add_f32 v[168:169], v[68:69], v[168:169]
	v_pk_add_f32 v[130:131], v[66:67], v[130:131]
	v_pk_add_f32 v[128:129], v[64:65], v[128:129]
	global_store_dwordx4 v179, v[168:171], s[58:59] offset:512 nt
	global_store_dwordx4 v179, v[128:131], s[58:59] offset:528 nt
	global_load_dwordx4 v[68:71], v183, s[58:59] offset:512 nt
	global_load_dwordx4 v[64:67], v183, s[58:59] offset:528 nt
	s_waitcnt vmcnt(28)
	v_pk_add_f32 v[126:127], v[62:63], v[126:127]
	v_pk_add_f32 v[124:125], v[60:61], v[124:125]
	v_pk_add_f32 v[122:123], v[58:59], v[122:123]
	v_pk_add_f32 v[120:121], v[56:57], v[120:121]
	global_store_dwordx4 v180, v[124:127], s[58:59] nt
	global_store_dwordx4 v180, v[120:123], s[58:59] offset:16 nt
	s_waitcnt vmcnt(26)
	v_pk_add_f32 v[118:119], v[54:55], v[118:119]
	v_pk_add_f32 v[116:117], v[52:53], v[116:117]
	v_pk_add_f32 v[114:115], v[50:51], v[114:115]
	v_pk_add_f32 v[112:113], v[48:49], v[112:113]
	global_store_dwordx4 v180, v[116:119], s[58:59] offset:512 nt
	global_store_dwordx4 v180, v[112:115], s[58:59] offset:528 nt
	s_waitcnt vmcnt(24)
	v_pk_add_f32 v[110:111], v[46:47], v[110:111]
	v_pk_add_f32 v[108:109], v[44:45], v[108:109]
	v_pk_add_f32 v[106:107], v[42:43], v[106:107]
	v_pk_add_f32 v[104:105], v[40:41], v[104:105]
	global_store_dwordx4 v181, v[108:111], s[58:59] nt
	global_store_dwordx4 v181, v[104:107], s[58:59] offset:16 nt
	s_waitcnt vmcnt(22)
	v_pk_add_f32 v[102:103], v[38:39], v[102:103]
	v_pk_add_f32 v[100:101], v[36:37], v[100:101]
	v_pk_add_f32 v[98:99], v[34:35], v[98:99]
	v_pk_add_f32 v[96:97], v[32:33], v[96:97]
	global_store_dwordx4 v181, v[100:103], s[58:59] offset:512 nt
	global_store_dwordx4 v181, v[96:99], s[58:59] offset:528 nt
	s_waitcnt vmcnt(20)
	v_pk_add_f32 v[94:95], v[30:31], v[94:95]
	v_pk_add_f32 v[92:93], v[28:29], v[92:93]
	v_pk_add_f32 v[90:91], v[26:27], v[90:91]
	v_pk_add_f32 v[88:89], v[24:25], v[88:89]
	global_store_dwordx4 v182, v[92:95], s[58:59] nt
	global_store_dwordx4 v182, v[88:91], s[58:59] offset:16 nt
	s_waitcnt vmcnt(18)
	v_pk_add_f32 v[86:87], v[22:23], v[86:87]
	v_pk_add_f32 v[84:85], v[20:21], v[84:85]
	v_pk_add_f32 v[82:83], v[18:19], v[82:83]
	v_pk_add_f32 v[80:81], v[16:17], v[80:81]
	global_store_dwordx4 v182, v[84:87], s[58:59] offset:512 nt
	global_store_dwordx4 v182, v[80:83], s[58:59] offset:528 nt
	s_waitcnt vmcnt(16)
	v_pk_add_f32 v[78:79], v[14:15], v[78:79]
	v_pk_add_f32 v[76:77], v[12:13], v[76:77]
	v_pk_add_f32 v[74:75], v[10:11], v[74:75]
	v_pk_add_f32 v[72:73], v[8:9], v[72:73]
	global_store_dwordx4 v183, v[76:79], s[58:59] nt
	global_store_dwordx4 v183, v[72:75], s[58:59] offset:16 nt
	s_waitcnt vmcnt(14)
	v_pk_add_f32 v[70:71], v[6:7], v[70:71]
	v_pk_add_f32 v[68:69], v[4:5], v[68:69]
	v_pk_add_f32 v[66:67], v[2:3], v[66:67]
	v_pk_add_f32 v[64:65], v[0:1], v[64:65]
	global_store_dwordx4 v183, v[68:71], s[58:59] offset:512 nt
	global_store_dwordx4 v183, v[64:67], s[58:59] offset:528 nt
	s_branch .LBB0_567
.Lepi5:
	v_lshlrev_b32_e32 v176, 12, v150
	v_lshl_add_u32 v176, v148, 2, v176
	v_add_u32_e32 v177, 0x10000, v176
	v_add_u32_e32 v178, 0x20000, v176
	v_add_u32_e32 v179, 0x30000, v176
	v_add_u32_e32 v180, 0x80000, v176
	v_add_u32_e32 v181, 0x90000, v176
	v_add_u32_e32 v182, 0xa0000, v176
	v_add_u32_e32 v183, 0xb0000, v176
	global_load_dwordx4 v[184:187], v176, s[24:25] nt
	global_load_dwordx4 v[188:191], v176, s[24:25] offset:16 nt
	global_load_dwordx4 v[192:195], v176, s[24:25] offset:512 nt
	global_load_dwordx4 v[196:199], v176, s[24:25] offset:528 nt
	global_load_dwordx4 v[200:203], v177, s[24:25] nt
	global_load_dwordx4 v[204:207], v177, s[24:25] offset:16 nt
	global_load_dwordx4 v[208:211], v177, s[24:25] offset:512 nt
	global_load_dwordx4 v[212:215], v177, s[24:25] offset:528 nt
	global_load_dwordx4 v[216:219], v178, s[24:25] nt
	global_load_dwordx4 v[220:223], v178, s[24:25] offset:16 nt
	global_load_dwordx4 v[152:155], v178, s[24:25] offset:512 nt
	global_load_dwordx4 v[156:159], v178, s[24:25] offset:528 nt
	global_load_dwordx4 v[160:163], v179, s[24:25] nt
	global_load_dwordx4 v[164:167], v179, s[24:25] offset:16 nt
	global_load_dwordx4 v[168:171], v179, s[24:25] offset:512 nt
	global_load_dwordx4 v[128:131], v179, s[24:25] offset:528 nt
	s_waitcnt vmcnt(14)
	v_pk_add_f32 v[186:187], v[126:127], v[186:187]
	v_pk_add_f32 v[184:185], v[124:125], v[184:185]
	v_pk_add_f32 v[190:191], v[122:123], v[190:191]
	v_pk_add_f32 v[188:189], v[120:121], v[188:189]
	global_store_dwordx4 v176, v[184:187], s[58:59]
	global_store_dwordx4 v176, v[188:191], s[58:59] offset:16
	global_load_dwordx4 v[124:127], v180, s[24:25] nt
	global_load_dwordx4 v[120:123], v180, s[24:25] offset:16 nt
	s_waitcnt vmcnt(16)
	v_pk_add_f32 v[194:195], v[118:119], v[194:195]
	v_pk_add_f32 v[192:193], v[116:117], v[192:193]
	v_pk_add_f32 v[198:199], v[114:115], v[198:199]
	v_pk_add_f32 v[196:197], v[112:113], v[196:197]
	global_store_dwordx4 v176, v[192:195], s[58:59] offset:512
	global_store_dwordx4 v176, v[196:199], s[58:59] offset:528
	global_load_dwordx4 v[116:119], v180, s[24:25] offset:512 nt
	global_load_dwordx4 v[112:115], v180, s[24:25] offset:528 nt
	s_waitcnt vmcnt(18)
	v_pk_add_f32 v[202:203], v[110:111], v[202:203]
	v_pk_add_f32 v[200:201], v[108:109], v[200:201]
	v_pk_add_f32 v[206:207], v[106:107], v[206:207]
	v_pk_add_f32 v[204:205], v[104:105], v[204:205]
	global_store_dwordx4 v177, v[200:203], s[58:59]
	global_store_dwordx4 v177, v[204:207], s[58:59] offset:16
	global_load_dwordx4 v[108:111], v181, s[24:25] nt
	global_load_dwordx4 v[104:107], v181, s[24:25] offset:16 nt
	s_waitcnt vmcnt(20)
	v_pk_add_f32 v[210:211], v[102:103], v[210:211]
	v_pk_add_f32 v[208:209], v[100:101], v[208:209]
	v_pk_add_f32 v[214:215], v[98:99], v[214:215]
	v_pk_add_f32 v[212:213], v[96:97], v[212:213]
	global_store_dwordx4 v177, v[208:211], s[58:59] offset:512
	global_store_dwordx4 v177, v[212:215], s[58:59] offset:528
	global_load_dwordx4 v[100:103], v181, s[24:25] offset:512 nt
	global_load_dwordx4 v[96:99], v181, s[24:25] offset:528 nt
	s_waitcnt vmcnt(22)
	v_pk_add_f32 v[218:219], v[94:95], v[218:219]
	v_pk_add_f32 v[216:217], v[92:93], v[216:217]
	v_pk_add_f32 v[222:223], v[90:91], v[222:223]
	v_pk_add_f32 v[220:221], v[88:89], v[220:221]
	global_store_dwordx4 v178, v[216:219], s[58:59]
	global_store_dwordx4 v178, v[220:223], s[58:59] offset:16
	global_load_dwordx4 v[92:95], v182, s[24:25] nt
	global_load_dwordx4 v[88:91], v182, s[24:25] offset:16 nt
	s_waitcnt vmcnt(24)
	v_pk_add_f32 v[154:155], v[86:87], v[154:155]
	v_pk_add_f32 v[152:153], v[84:85], v[152:153]
	v_pk_add_f32 v[158:159], v[82:83], v[158:159]
	v_pk_add_f32 v[156:157], v[80:81], v[156:157]
	global_store_dwordx4 v178, v[152:155], s[58:59] offset:512
	global_store_dwordx4 v178, v[156:159], s[58:59] offset:528
	global_load_dwordx4 v[84:87], v182, s[24:25] offset:512 nt
	global_load_dwordx4 v[80:83], v182, s[24:25] offset:528 nt
	s_waitcnt vmcnt(26)
	v_pk_add_f32 v[162:163], v[78:79], v[162:163]
	v_pk_add_f32 v[160:161], v[76:77], v[160:161]
	v_pk_add_f32 v[166:167], v[74:75], v[166:167]
	v_pk_add_f32 v[164:165], v[72:73], v[164:165]
	global_store_dwordx4 v179, v[160:163], s[58:59]
	global_store_dwordx4 v179, v[164:167], s[58:59] offset:16
	global_load_dwordx4 v[76:79], v183, s[24:25] nt
	global_load_dwordx4 v[72:75], v183, s[24:25] offset:16 nt
	s_waitcnt vmcnt(28)
	v_pk_add_f32 v[170:171], v[70:71], v[170:171]
	v_pk_add_f32 v[168:169], v[68:69], v[168:169]
	v_pk_add_f32 v[130:131], v[66:67], v[130:131]
	v_pk_add_f32 v[128:129], v[64:65], v[128:129]
	global_store_dwordx4 v179, v[168:171], s[58:59] offset:512
	global_store_dwordx4 v179, v[128:131], s[58:59] offset:528
	global_load_dwordx4 v[68:71], v183, s[24:25] offset:512 nt
	global_load_dwordx4 v[64:67], v183, s[24:25] offset:528 nt
	s_waitcnt vmcnt(28)
	v_pk_add_f32 v[126:127], v[62:63], v[126:127]
	v_pk_add_f32 v[124:125], v[60:61], v[124:125]
	v_pk_add_f32 v[122:123], v[58:59], v[122:123]
	v_pk_add_f32 v[120:121], v[56:57], v[120:121]
	global_store_dwordx4 v180, v[124:127], s[58:59]
	global_store_dwordx4 v180, v[120:123], s[58:59] offset:16
	s_waitcnt vmcnt(26)
	v_pk_add_f32 v[118:119], v[54:55], v[118:119]
	v_pk_add_f32 v[116:117], v[52:53], v[116:117]
	v_pk_add_f32 v[114:115], v[50:51], v[114:115]
	v_pk_add_f32 v[112:113], v[48:49], v[112:113]
	global_store_dwordx4 v180, v[116:119], s[58:59] offset:512
	global_store_dwordx4 v180, v[112:115], s[58:59] offset:528
	s_waitcnt vmcnt(24)
	v_pk_add_f32 v[110:111], v[46:47], v[110:111]
	v_pk_add_f32 v[108:109], v[44:45], v[108:109]
	v_pk_add_f32 v[106:107], v[42:43], v[106:107]
	v_pk_add_f32 v[104:105], v[40:41], v[104:105]
	global_store_dwordx4 v181, v[108:111], s[58:59]
	global_store_dwordx4 v181, v[104:107], s[58:59] offset:16
	s_waitcnt vmcnt(22)
	v_pk_add_f32 v[102:103], v[38:39], v[102:103]
	v_pk_add_f32 v[100:101], v[36:37], v[100:101]
	v_pk_add_f32 v[98:99], v[34:35], v[98:99]
	v_pk_add_f32 v[96:97], v[32:33], v[96:97]
	global_store_dwordx4 v181, v[100:103], s[58:59] offset:512
	global_store_dwordx4 v181, v[96:99], s[58:59] offset:528
	s_waitcnt vmcnt(20)
	v_pk_add_f32 v[94:95], v[30:31], v[94:95]
	v_pk_add_f32 v[92:93], v[28:29], v[92:93]
	v_pk_add_f32 v[90:91], v[26:27], v[90:91]
	v_pk_add_f32 v[88:89], v[24:25], v[88:89]
	global_store_dwordx4 v182, v[92:95], s[58:59]
	global_store_dwordx4 v182, v[88:91], s[58:59] offset:16
	s_waitcnt vmcnt(18)
	v_pk_add_f32 v[86:87], v[22:23], v[86:87]
	v_pk_add_f32 v[84:85], v[20:21], v[84:85]
	v_pk_add_f32 v[82:83], v[18:19], v[82:83]
	v_pk_add_f32 v[80:81], v[16:17], v[80:81]
	global_store_dwordx4 v182, v[84:87], s[58:59] offset:512
	global_store_dwordx4 v182, v[80:83], s[58:59] offset:528
	s_waitcnt vmcnt(16)
	v_pk_add_f32 v[78:79], v[14:15], v[78:79]
	v_pk_add_f32 v[76:77], v[12:13], v[76:77]
	v_pk_add_f32 v[74:75], v[10:11], v[74:75]
	v_pk_add_f32 v[72:73], v[8:9], v[72:73]
	global_store_dwordx4 v183, v[76:79], s[58:59]
	global_store_dwordx4 v183, v[72:75], s[58:59] offset:16
	s_waitcnt vmcnt(14)
	v_pk_add_f32 v[70:71], v[6:7], v[70:71]
	v_pk_add_f32 v[68:69], v[4:5], v[68:69]
	v_pk_add_f32 v[66:67], v[2:3], v[66:67]
	v_pk_add_f32 v[64:65], v[0:1], v[64:65]
	global_store_dwordx4 v183, v[68:71], s[58:59] offset:512
	global_store_dwordx4 v183, v[64:67], s[58:59] offset:528
	s_branch .LBB0_567
